# layer-1 w_out transposes deferred to the P6 head now run on even-numbered workgroups (even XCDs) instead of odd
# speedup vs baseline: 1.0050x; 1.0020x over previous
.LBB0_783:
	s_or_b64 exec, exec, s[0:1]
	s_bitcmp1_b32 s2, 0
	s_cbranch_scc1 .Ldf_skip_p6
	v_writelane_b32 v234, s0, 0
	v_writelane_b32 v234, s1, 1
	v_writelane_b32 v234, s2, 2
	v_writelane_b32 v234, s3, 3
	v_writelane_b32 v234, s4, 4
	v_writelane_b32 v234, s5, 5
	v_writelane_b32 v234, s6, 6
	v_writelane_b32 v234, s7, 7
	v_writelane_b32 v234, s8, 8
	v_writelane_b32 v234, s9, 9
	v_writelane_b32 v234, s10, 10
	v_writelane_b32 v234, s11, 11
	v_writelane_b32 v234, s12, 12
	v_writelane_b32 v234, s13, 13
	v_writelane_b32 v234, s14, 14
	v_writelane_b32 v234, s15, 15
	v_writelane_b32 v234, s16, 16
	v_writelane_b32 v234, s17, 17
	v_writelane_b32 v234, s18, 18
	v_writelane_b32 v234, s19, 19
	v_writelane_b32 v234, s20, 20
	v_writelane_b32 v234, s21, 21
	v_writelane_b32 v234, s22, 22
	v_writelane_b32 v234, s23, 23
	v_writelane_b32 v234, s24, 24
	v_writelane_b32 v234, s25, 25
	v_writelane_b32 v234, s26, 26
	v_writelane_b32 v234, s27, 27
	v_writelane_b32 v234, s28, 28
	v_writelane_b32 v234, s29, 29
	v_writelane_b32 v234, s30, 30
	v_writelane_b32 v234, s31, 31
	v_writelane_b32 v234, s32, 32
	v_writelane_b32 v234, s33, 33
	v_writelane_b32 v234, s34, 34
	v_writelane_b32 v234, s35, 35
	v_writelane_b32 v234, s36, 36
	v_writelane_b32 v234, s37, 37
	v_writelane_b32 v234, s38, 38
	v_writelane_b32 v234, s39, 39
	v_writelane_b32 v234, s40, 40
	v_writelane_b32 v234, s41, 41
	v_writelane_b32 v234, s42, 42
	v_writelane_b32 v234, s43, 43
	v_writelane_b32 v234, s44, 44
	v_writelane_b32 v234, s45, 45
	v_writelane_b32 v234, s46, 46
	v_writelane_b32 v234, s47, 47
	v_writelane_b32 v234, s48, 48
	v_writelane_b32 v234, s49, 49
	v_writelane_b32 v234, s50, 50
	v_writelane_b32 v234, s51, 51
	v_writelane_b32 v234, s52, 52
	v_writelane_b32 v234, s53, 53
	v_writelane_b32 v234, s54, 54
	v_writelane_b32 v234, s55, 55
	v_writelane_b32 v234, s56, 56
	v_writelane_b32 v234, s57, 57
	v_writelane_b32 v234, s58, 58
	v_writelane_b32 v234, s59, 59
	v_writelane_b32 v234, s60, 60
	v_writelane_b32 v234, s61, 61
	v_writelane_b32 v234, s62, 62
	v_writelane_b32 v234, s63, 63
	v_writelane_b32 v235, s64, 0
	v_writelane_b32 v235, s65, 1
	v_writelane_b32 v235, s66, 2
	v_writelane_b32 v235, s67, 3
	v_writelane_b32 v235, s68, 4
	v_writelane_b32 v235, s69, 5
	v_writelane_b32 v235, s70, 6
	v_writelane_b32 v235, s71, 7
	v_writelane_b32 v235, s72, 8
	v_writelane_b32 v235, s73, 9
	v_writelane_b32 v235, s74, 10
	v_writelane_b32 v235, s75, 11
	v_writelane_b32 v235, s76, 12
	v_writelane_b32 v235, s77, 13
	v_writelane_b32 v235, s78, 14
	v_writelane_b32 v235, s79, 15
	v_writelane_b32 v235, s80, 16
	v_writelane_b32 v235, s81, 17
	v_writelane_b32 v235, s82, 18
	v_writelane_b32 v235, s83, 19
	v_writelane_b32 v235, s84, 20
	v_writelane_b32 v235, s85, 21
	v_writelane_b32 v235, s86, 22
	v_writelane_b32 v235, s87, 23
	v_writelane_b32 v235, s88, 24
	v_writelane_b32 v235, s89, 25
	v_writelane_b32 v235, s90, 26
	v_writelane_b32 v235, s91, 27
	v_writelane_b32 v235, s92, 28
	v_writelane_b32 v235, s93, 29
	v_writelane_b32 v235, s94, 30
	v_writelane_b32 v235, s95, 31
	v_writelane_b32 v235, s96, 32
	v_writelane_b32 v235, s97, 33
	v_writelane_b32 v235, vcc_lo, 34
	v_writelane_b32 v235, vcc_hi, 35
	v_readlane_b32 s70, v233, 45
	v_readlane_b32 s71, v233, 46
	s_add_u32 s22, s92, 0x4500000
	s_addc_u32 s23, s93, 0
	s_add_u32 s40, s92, 0x1400000
	s_addc_u32 s41, s93, 0
	v_mov_b32_e32 v0, v210
	s_nop 0
	v_readfirstlane_b32 s1, v0
	s_nop 3
	s_ashr_i32 s13, s1, 6
	s_lshr_b32 s0, s2, 1
	s_lshl_b32 s0, s0, 3
	s_add_i32 s33, s13, s0
	s_addk_i32 s33, 0x1c00
	s_movk_i32 s12, 0x80
	s_movk_i32 s101, 0x2400
	s_mov_b32 s100, 5
	s_branch .Lp3t_setup
